# v070 plus: the last tile of each FFN-up workgroup stores H with plain stores (EXEC-masked dual stores), other tiles write-through
# baseline (speedup 1.0000x reference)
; DI unsigned pk2(float lo, float hi) { f32x2 v = {lo, hi}; return __builtin_bit_cast(unsigned, __builtin_convertvector(v, bf2_t)); }
;     DI void operator()(const f32x4 (&acc)[2][2][4][2], const Unit& u, int wr, int wc, int fr, int fq) const {
;         const int row0 = u.pm * BM + wr * 64 + fr, col0 = u.pn * HALF + wc * 32 + 8 * fq;
; #pragma unroll
;         for (int ai = 0; ai < 2; ++ai)
; #pragma unroll
;             for (int m = 0; m < 4; ++m) {
;                 bf16_t* rowp = H + (size_t)(row0 + ai * HALF + m * 16) * ldh + col0;
;                 const f32x4 g0 = acc[ai][0][m][0], g1 = acc[ai][0][m][1], u0 = acc[ai][1][m][0], u1 = acc[ai][1][m][1];
;                 const f32x2 ha = swiglu_pk((f32x2){g0[0], g0[1]}, (f32x2){u0[0], u0[1]}), hb = swiglu_pk((f32x2){g0[2], g0[3]}, (f32x2){u0[2], u0[3]});
;                 const f32x2 hc = swiglu_pk((f32x2){g1[0], g1[1]}, (f32x2){u1[0], u1[1]}), hd = swiglu_pk((f32x2){g1[2], g1[3]}, (f32x2){u1[2], u1[3]});
;                 u32x4 w; w.x = pk2(ha.x, ha.y); w.y = pk2(hb.x, hb.y); w.z = pk2(hc.x, hc.y); w.w = pk2(hd.x, hd.y);
;                 *(u32x4*)rowp = w;
;             }
.LBB0_243:
	s_not_b64 s[100:101], s[40:41]
	v_pk_mul_f32 v[152:153], v[126:127], s[30:31] op_sel_hi:[1,0]
	v_lshl_or_b32 v142, s50, 7, v146
	v_exp_f32_e32 v152, v152
	v_exp_f32_e32 v153, v153
	v_lshl_add_u32 v148, s52, 8, v144
	v_ashrrev_i32_e32 v143, 31, v142
	v_mov_b64_e32 v[140:141], s[80:81]
	v_pk_add_f32 v[152:153], v[152:153], 1.0 op_sel_hi:[1,0]
	v_mad_i64_i32 v[150:151], s[20:21], v148, s15, v[140:141]
	v_rcp_f32_e32 v152, v152
	v_rcp_f32_e32 v153, v153
	v_lshlrev_b64 v[142:143], 1, v[142:143]
	v_lshl_add_u64 v[150:151], v[150:151], 0, v[142:143]
	s_andn2_b64 vcc, exec, s[40:41]
	v_pk_mul_f32 v[126:127], v[126:127], v[152:153]
	s_nop 0
	v_pk_mul_f32 v[122:123], v[126:127], v[122:123]
	v_pk_mul_f32 v[126:127], v[128:129], s[30:31] op_sel_hi:[1,0]
	s_nop 0
	v_exp_f32_e32 v126, v126
	v_exp_f32_e32 v127, v127
	s_nop 0
	v_pk_add_f32 v[126:127], v[126:127], 1.0 op_sel_hi:[1,0]
	s_nop 0
	v_rcp_f32_e32 v126, v126
	v_rcp_f32_e32 v127, v127
	s_nop 0
	v_pk_mul_f32 v[126:127], v[128:129], v[126:127]
	s_nop 0
	v_pk_mul_f32 v[124:125], v[126:127], v[124:125]
	v_pk_mul_f32 v[126:127], v[118:119], s[30:31] op_sel_hi:[1,0]
	s_nop 0
	v_exp_f32_e32 v126, v126
	v_exp_f32_e32 v127, v127
	s_nop 0
	v_pk_add_f32 v[126:127], v[126:127], 1.0 op_sel_hi:[1,0]
	s_nop 0
	v_rcp_f32_e32 v126, v126
	v_rcp_f32_e32 v127, v127
	s_nop 0
	v_pk_mul_f32 v[118:119], v[118:119], v[126:127]
	s_nop 0
	v_pk_mul_f32 v[118:119], v[118:119], v[114:115]
	v_pk_mul_f32 v[114:115], v[120:121], s[30:31] op_sel_hi:[1,0]
	s_nop 0
	v_exp_f32_e32 v114, v114
	v_exp_f32_e32 v115, v115
	s_nop 0
	v_pk_add_f32 v[114:115], v[114:115], 1.0 op_sel_hi:[1,0]
	s_nop 0
	v_rcp_f32_e32 v114, v114
	v_rcp_f32_e32 v115, v115
	s_nop 0
	v_pk_mul_f32 v[114:115], v[120:121], v[114:115]
	s_nop 0
	v_pk_mul_f32 v[120:121], v[114:115], v[116:117]
	v_cvt_pk_bf16_f32 v114, v122, v123
	v_cvt_pk_bf16_f32 v115, v124, v125
	v_cvt_pk_bf16_f32 v116, v118, v119
	v_cvt_pk_bf16_f32 v117, v120, v121
	s_mov_b64 exec, s[40:41]
	global_store_dwordx4 v[150:151], v[114:117], off sc1
	s_mov_b64 exec, s[100:101]
	global_store_dwordx4 v[150:151], v[114:117], off
	s_mov_b64 exec, -1
	s_nop 1
	v_pk_mul_f32 v[116:117], v[110:111], s[30:31] op_sel_hi:[1,0]
	v_or_b32_e32 v114, 16, v148
	v_exp_f32_e32 v116, v116
	v_exp_f32_e32 v117, v117
	v_mad_i64_i32 v[114:115], s[20:21], v114, s15, v[140:141]
	v_lshl_add_u64 v[114:115], v[114:115], 0, v[142:143]
	v_pk_add_f32 v[116:117], v[116:117], 1.0 op_sel_hi:[1,0]
	s_nop 0
	v_rcp_f32_e32 v116, v116
	v_rcp_f32_e32 v117, v117
	s_nop 0
	v_pk_mul_f32 v[110:111], v[110:111], v[116:117]
	s_nop 0
	v_pk_mul_f32 v[106:107], v[110:111], v[106:107]
	v_pk_mul_f32 v[110:111], v[112:113], s[30:31] op_sel_hi:[1,0]
	s_nop 0
	v_exp_f32_e32 v110, v110
	v_exp_f32_e32 v111, v111
	s_nop 0
	v_pk_add_f32 v[110:111], v[110:111], 1.0 op_sel_hi:[1,0]
	s_nop 0
	v_rcp_f32_e32 v110, v110
	v_rcp_f32_e32 v111, v111
	s_nop 0
	v_pk_mul_f32 v[110:111], v[112:113], v[110:111]
	s_nop 0
	v_pk_mul_f32 v[108:109], v[110:111], v[108:109]
	v_pk_mul_f32 v[110:111], v[102:103], s[30:31] op_sel_hi:[1,0]
	s_nop 0
	v_exp_f32_e32 v110, v110
	v_exp_f32_e32 v111, v111
	s_nop 0
	v_pk_add_f32 v[110:111], v[110:111], 1.0 op_sel_hi:[1,0]
	s_nop 0
	v_rcp_f32_e32 v110, v110
	v_rcp_f32_e32 v111, v111
	s_nop 0
	v_pk_mul_f32 v[102:103], v[102:103], v[110:111]
	s_nop 0
	v_pk_mul_f32 v[102:103], v[102:103], v[98:99]
	v_pk_mul_f32 v[98:99], v[104:105], s[30:31] op_sel_hi:[1,0]
	s_nop 0
	v_exp_f32_e32 v98, v98
	v_exp_f32_e32 v99, v99
	s_nop 0
	v_pk_add_f32 v[98:99], v[98:99], 1.0 op_sel_hi:[1,0]
	s_nop 0
	v_rcp_f32_e32 v98, v98
	v_rcp_f32_e32 v99, v99
	s_nop 0
	v_pk_mul_f32 v[98:99], v[104:105], v[98:99]
	s_nop 0
	v_pk_mul_f32 v[104:105], v[98:99], v[100:101]
	v_cvt_pk_bf16_f32 v98, v106, v107
	v_cvt_pk_bf16_f32 v99, v108, v109
	v_cvt_pk_bf16_f32 v100, v102, v103
	v_cvt_pk_bf16_f32 v101, v104, v105
	s_mov_b64 exec, s[40:41]
	global_store_dwordx4 v[114:115], v[98:101], off sc1
	s_mov_b64 exec, s[100:101]
	global_store_dwordx4 v[114:115], v[98:101], off
	s_mov_b64 exec, -1
	s_nop 1
	v_pk_mul_f32 v[100:101], v[92:93], s[30:31] op_sel_hi:[1,0]
	v_or_b32_e32 v98, 32, v148
	v_exp_f32_e32 v100, v100
	v_exp_f32_e32 v101, v101
	v_mad_i64_i32 v[98:99], s[20:21], v98, s15, v[140:141]
	v_lshl_add_u64 v[98:99], v[98:99], 0, v[142:143]
	v_pk_add_f32 v[100:101], v[100:101], 1.0 op_sel_hi:[1,0]
	s_nop 0
	v_rcp_f32_e32 v100, v100
	v_rcp_f32_e32 v101, v101
	s_nop 0
	v_pk_mul_f32 v[92:93], v[92:93], v[100:101]
	s_nop 0
	v_pk_mul_f32 v[88:89], v[92:93], v[88:89]
	v_pk_mul_f32 v[92:93], v[94:95], s[30:31] op_sel_hi:[1,0]
	s_nop 0
	v_exp_f32_e32 v92, v92
	v_exp_f32_e32 v93, v93
	s_nop 0
	v_pk_add_f32 v[92:93], v[92:93], 1.0 op_sel_hi:[1,0]
	s_nop 0
	v_rcp_f32_e32 v92, v92
	v_rcp_f32_e32 v93, v93
	s_nop 0
	v_pk_mul_f32 v[92:93], v[94:95], v[92:93]
	s_nop 0
	v_pk_mul_f32 v[90:91], v[92:93], v[90:91]
	v_pk_mul_f32 v[92:93], v[84:85], s[30:31] op_sel_hi:[1,0]
	s_nop 0
	v_exp_f32_e32 v92, v92
	v_exp_f32_e32 v93, v93
	s_nop 0
	v_pk_add_f32 v[92:93], v[92:93], 1.0 op_sel_hi:[1,0]
	s_nop 0
	v_rcp_f32_e32 v92, v92
	v_rcp_f32_e32 v93, v93
	s_nop 0
	v_pk_mul_f32 v[84:85], v[84:85], v[92:93]
	s_nop 0
	v_pk_mul_f32 v[84:85], v[84:85], v[80:81]
	v_pk_mul_f32 v[80:81], v[86:87], s[30:31] op_sel_hi:[1,0]
	s_nop 0
	v_exp_f32_e32 v80, v80
	v_exp_f32_e32 v81, v81
	s_nop 0
	v_pk_add_f32 v[80:81], v[80:81], 1.0 op_sel_hi:[1,0]
	s_nop 0
	v_rcp_f32_e32 v80, v80
	v_rcp_f32_e32 v81, v81
	s_nop 0
	v_pk_mul_f32 v[80:81], v[86:87], v[80:81]
	s_nop 0
	v_pk_mul_f32 v[86:87], v[80:81], v[82:83]
	v_cvt_pk_bf16_f32 v80, v88, v89
	v_cvt_pk_bf16_f32 v81, v90, v91
	v_cvt_pk_bf16_f32 v82, v84, v85
; DI unsigned pk2(float lo, float hi) { f32x2 v = {lo, hi}; return __builtin_bit_cast(unsigned, __builtin_convertvector(v, bf2_t)); }
;     DI void operator()(const f32x4 (&acc)[2][2][4][2], const Unit& u, int wr, int wc, int fr, int fq) const {
;         const int row0 = u.pm * BM + wr * 64 + fr, col0 = u.pn * HALF + wc * 32 + 8 * fq;
; #pragma unroll
;         for (int ai = 0; ai < 2; ++ai)
; #pragma unroll
;             for (int m = 0; m < 4; ++m) {
;                 bf16_t* rowp = H + (size_t)(row0 + ai * HALF + m * 16) * ldh + col0;
;                 const f32x4 g0 = acc[ai][0][m][0], g1 = acc[ai][0][m][1], u0 = acc[ai][1][m][0], u1 = acc[ai][1][m][1];
;                 const f32x2 ha = swiglu_pk((f32x2){g0[0], g0[1]}, (f32x2){u0[0], u0[1]}), hb = swiglu_pk((f32x2){g0[2], g0[3]}, (f32x2){u0[2], u0[3]});
;                 const f32x2 hc = swiglu_pk((f32x2){g1[0], g1[1]}, (f32x2){u1[0], u1[1]}), hd = swiglu_pk((f32x2){g1[2], g1[3]}, (f32x2){u1[2], u1[3]});
;                 u32x4 w; w.x = pk2(ha.x, ha.y); w.y = pk2(hb.x, hb.y); w.z = pk2(hc.x, hc.y); w.w = pk2(hd.x, hd.y);
;                 *(u32x4*)rowp = w;
;             }
	v_cvt_pk_bf16_f32 v83, v86, v87
	s_mov_b64 exec, s[40:41]
	global_store_dwordx4 v[98:99], v[80:83], off sc1
	s_mov_b64 exec, s[100:101]
	global_store_dwordx4 v[98:99], v[80:83], off
	s_mov_b64 exec, -1
	s_nop 1
	v_pk_mul_f32 v[82:83], v[76:77], s[30:31] op_sel_hi:[1,0]
	v_or_b32_e32 v80, 48, v148
	v_exp_f32_e32 v82, v82
	v_exp_f32_e32 v83, v83
	v_mad_i64_i32 v[80:81], s[20:21], v80, s15, v[140:141]
	v_lshl_add_u64 v[80:81], v[80:81], 0, v[142:143]
	v_pk_add_f32 v[82:83], v[82:83], 1.0 op_sel_hi:[1,0]
	s_nop 0
	v_rcp_f32_e32 v82, v82
	v_rcp_f32_e32 v83, v83
	s_nop 0
	v_pk_mul_f32 v[76:77], v[76:77], v[82:83]
	s_nop 0
	v_pk_mul_f32 v[72:73], v[76:77], v[72:73]
	v_pk_mul_f32 v[76:77], v[78:79], s[30:31] op_sel_hi:[1,0]
	s_nop 0
	v_exp_f32_e32 v76, v76
	v_exp_f32_e32 v77, v77
	s_nop 0
	v_pk_add_f32 v[76:77], v[76:77], 1.0 op_sel_hi:[1,0]
	s_nop 0
	v_rcp_f32_e32 v76, v76
	v_rcp_f32_e32 v77, v77
	s_nop 0
	v_pk_mul_f32 v[76:77], v[78:79], v[76:77]
	s_nop 0
	v_pk_mul_f32 v[74:75], v[76:77], v[74:75]
	v_pk_mul_f32 v[76:77], v[68:69], s[30:31] op_sel_hi:[1,0]
	s_nop 0
	v_exp_f32_e32 v76, v76
	v_exp_f32_e32 v77, v77
	s_nop 0
	v_pk_add_f32 v[76:77], v[76:77], 1.0 op_sel_hi:[1,0]
	s_nop 0
	v_rcp_f32_e32 v76, v76
	v_rcp_f32_e32 v77, v77
	s_nop 0
	v_pk_mul_f32 v[68:69], v[68:69], v[76:77]
	s_nop 0
	v_pk_mul_f32 v[68:69], v[68:69], v[64:65]
	v_pk_mul_f32 v[64:65], v[70:71], s[30:31] op_sel_hi:[1,0]
	s_nop 0
	v_exp_f32_e32 v64, v64
	v_exp_f32_e32 v65, v65
	s_nop 0
	v_pk_add_f32 v[64:65], v[64:65], 1.0 op_sel_hi:[1,0]
	s_nop 0
	v_rcp_f32_e32 v64, v64
	v_rcp_f32_e32 v65, v65
	s_nop 0
	v_pk_mul_f32 v[64:65], v[70:71], v[64:65]
	s_nop 0
	v_pk_mul_f32 v[70:71], v[64:65], v[66:67]
	v_cvt_pk_bf16_f32 v64, v72, v73
	v_cvt_pk_bf16_f32 v65, v74, v75
	v_cvt_pk_bf16_f32 v66, v68, v69
	v_cvt_pk_bf16_f32 v67, v70, v71
	s_mov_b64 exec, s[40:41]
	global_store_dwordx4 v[80:81], v[64:67], off sc1
	s_mov_b64 exec, s[100:101]
	global_store_dwordx4 v[80:81], v[64:67], off
	s_mov_b64 exec, -1
	s_nop 1
	v_pk_mul_f32 v[66:67], v[60:61], s[30:31] op_sel_hi:[1,0]
	v_add_u32_e32 v64, 0x80, v148
	v_exp_f32_e32 v66, v66
	v_exp_f32_e32 v67, v67
	v_mad_i64_i32 v[64:65], s[20:21], v64, s15, v[140:141]
	v_lshl_add_u64 v[64:65], v[64:65], 0, v[142:143]
	v_pk_add_f32 v[66:67], v[66:67], 1.0 op_sel_hi:[1,0]
	s_nop 0
	v_rcp_f32_e32 v66, v66
	v_rcp_f32_e32 v67, v67
	s_nop 0
	v_pk_mul_f32 v[60:61], v[60:61], v[66:67]
	s_nop 0
	v_pk_mul_f32 v[56:57], v[60:61], v[56:57]
	v_pk_mul_f32 v[60:61], v[62:63], s[30:31] op_sel_hi:[1,0]
	s_nop 0
	v_exp_f32_e32 v60, v60
	v_exp_f32_e32 v61, v61
	s_nop 0
	v_pk_add_f32 v[60:61], v[60:61], 1.0 op_sel_hi:[1,0]
	s_nop 0
	v_rcp_f32_e32 v60, v60
	v_rcp_f32_e32 v61, v61
	s_nop 0
	v_pk_mul_f32 v[60:61], v[62:63], v[60:61]
	s_nop 0
	v_pk_mul_f32 v[58:59], v[60:61], v[58:59]
	v_pk_mul_f32 v[60:61], v[52:53], s[30:31] op_sel_hi:[1,0]
	s_nop 0
	v_exp_f32_e32 v60, v60
	v_exp_f32_e32 v61, v61
	s_nop 0
	v_pk_add_f32 v[60:61], v[60:61], 1.0 op_sel_hi:[1,0]
	s_nop 0
	v_rcp_f32_e32 v60, v60
	v_rcp_f32_e32 v61, v61
	s_nop 0
	v_pk_mul_f32 v[52:53], v[52:53], v[60:61]
	s_nop 0
	v_pk_mul_f32 v[52:53], v[52:53], v[48:49]
	v_pk_mul_f32 v[48:49], v[54:55], s[30:31] op_sel_hi:[1,0]
	s_nop 0
	v_exp_f32_e32 v48, v48
	v_exp_f32_e32 v49, v49
	s_nop 0
	v_pk_add_f32 v[48:49], v[48:49], 1.0 op_sel_hi:[1,0]
	s_nop 0
	v_rcp_f32_e32 v48, v48
	v_rcp_f32_e32 v49, v49
	s_nop 0
	v_pk_mul_f32 v[48:49], v[54:55], v[48:49]
	s_nop 0
	v_pk_mul_f32 v[54:55], v[48:49], v[50:51]
	v_cvt_pk_bf16_f32 v48, v56, v57
	v_cvt_pk_bf16_f32 v49, v58, v59
	v_cvt_pk_bf16_f32 v50, v52, v53
	v_cvt_pk_bf16_f32 v51, v54, v55
	s_mov_b64 exec, s[40:41]
	global_store_dwordx4 v[64:65], v[48:51], off sc1
	s_mov_b64 exec, s[100:101]
	global_store_dwordx4 v[64:65], v[48:51], off
	s_mov_b64 exec, -1
	s_nop 1
	v_pk_mul_f32 v[50:51], v[44:45], s[30:31] op_sel_hi:[1,0]
	v_add_u32_e32 v48, 0x90, v148
	v_exp_f32_e32 v50, v50
	v_exp_f32_e32 v51, v51
	v_mad_i64_i32 v[48:49], s[20:21], v48, s15, v[140:141]
	v_lshl_add_u64 v[48:49], v[48:49], 0, v[142:143]
	v_pk_add_f32 v[50:51], v[50:51], 1.0 op_sel_hi:[1,0]
	s_nop 0
	v_rcp_f32_e32 v50, v50
	v_rcp_f32_e32 v51, v51
	s_nop 0
	v_pk_mul_f32 v[44:45], v[44:45], v[50:51]
	s_nop 0
	v_pk_mul_f32 v[40:41], v[44:45], v[40:41]
	v_pk_mul_f32 v[44:45], v[46:47], s[30:31] op_sel_hi:[1,0]
	s_nop 0
	v_exp_f32_e32 v44, v44
	v_exp_f32_e32 v45, v45
	s_nop 0
	v_pk_add_f32 v[44:45], v[44:45], 1.0 op_sel_hi:[1,0]
	s_nop 0
	v_rcp_f32_e32 v44, v44
	v_rcp_f32_e32 v45, v45
	s_nop 0
	v_pk_mul_f32 v[44:45], v[46:47], v[44:45]
	s_nop 0
	v_pk_mul_f32 v[42:43], v[44:45], v[42:43]
; DI unsigned pk2(float lo, float hi) { f32x2 v = {lo, hi}; return __builtin_bit_cast(unsigned, __builtin_convertvector(v, bf2_t)); }
;     DI void operator()(const f32x4 (&acc)[2][2][4][2], const Unit& u, int wr, int wc, int fr, int fq) const {
;         const int row0 = u.pm * BM + wr * 64 + fr, col0 = u.pn * HALF + wc * 32 + 8 * fq;
; #pragma unroll
;         for (int ai = 0; ai < 2; ++ai)
; #pragma unroll
;             for (int m = 0; m < 4; ++m) {
;                 bf16_t* rowp = H + (size_t)(row0 + ai * HALF + m * 16) * ldh + col0;
;                 const f32x4 g0 = acc[ai][0][m][0], g1 = acc[ai][0][m][1], u0 = acc[ai][1][m][0], u1 = acc[ai][1][m][1];
;                 const f32x2 ha = swiglu_pk((f32x2){g0[0], g0[1]}, (f32x2){u0[0], u0[1]}), hb = swiglu_pk((f32x2){g0[2], g0[3]}, (f32x2){u0[2], u0[3]});
;                 const f32x2 hc = swiglu_pk((f32x2){g1[0], g1[1]}, (f32x2){u1[0], u1[1]}), hd = swiglu_pk((f32x2){g1[2], g1[3]}, (f32x2){u1[2], u1[3]});
;                 u32x4 w; w.x = pk2(ha.x, ha.y); w.y = pk2(hb.x, hb.y); w.z = pk2(hc.x, hc.y); w.w = pk2(hd.x, hd.y);
;                 *(u32x4*)rowp = w;
;             }
	v_pk_mul_f32 v[44:45], v[36:37], s[30:31] op_sel_hi:[1,0]
	s_nop 0
	v_exp_f32_e32 v44, v44
	v_exp_f32_e32 v45, v45
	s_nop 0
	v_pk_add_f32 v[44:45], v[44:45], 1.0 op_sel_hi:[1,0]
	s_nop 0
	v_rcp_f32_e32 v44, v44
	v_rcp_f32_e32 v45, v45
	s_nop 0
	v_pk_mul_f32 v[36:37], v[36:37], v[44:45]
	s_nop 0
	v_pk_mul_f32 v[36:37], v[36:37], v[32:33]
	v_pk_mul_f32 v[32:33], v[38:39], s[30:31] op_sel_hi:[1,0]
	s_nop 0
	v_exp_f32_e32 v32, v32
	v_exp_f32_e32 v33, v33
	s_nop 0
	v_pk_add_f32 v[32:33], v[32:33], 1.0 op_sel_hi:[1,0]
	s_nop 0
	v_rcp_f32_e32 v32, v32
	v_rcp_f32_e32 v33, v33
	s_nop 0
	v_pk_mul_f32 v[32:33], v[38:39], v[32:33]
	s_nop 0
	v_pk_mul_f32 v[38:39], v[32:33], v[34:35]
	v_cvt_pk_bf16_f32 v32, v40, v41
	v_cvt_pk_bf16_f32 v33, v42, v43
	v_cvt_pk_bf16_f32 v34, v36, v37
	v_cvt_pk_bf16_f32 v35, v38, v39
	s_mov_b64 exec, s[40:41]
	global_store_dwordx4 v[48:49], v[32:35], off sc1
	s_mov_b64 exec, s[100:101]
	global_store_dwordx4 v[48:49], v[32:35], off
	s_mov_b64 exec, -1
	s_nop 1
	v_pk_mul_f32 v[34:35], v[28:29], s[30:31] op_sel_hi:[1,0]
	v_add_u32_e32 v32, 0xa0, v148
	v_exp_f32_e32 v34, v34
	v_exp_f32_e32 v35, v35
	v_mad_i64_i32 v[32:33], s[20:21], v32, s15, v[140:141]
	v_lshl_add_u64 v[32:33], v[32:33], 0, v[142:143]
	v_pk_add_f32 v[34:35], v[34:35], 1.0 op_sel_hi:[1,0]
	s_nop 0
	v_rcp_f32_e32 v34, v34
	v_rcp_f32_e32 v35, v35
	s_nop 0
	v_pk_mul_f32 v[28:29], v[28:29], v[34:35]
	s_nop 0
	v_pk_mul_f32 v[24:25], v[28:29], v[24:25]
	v_pk_mul_f32 v[28:29], v[30:31], s[30:31] op_sel_hi:[1,0]
	s_nop 0
	v_exp_f32_e32 v28, v28
	v_exp_f32_e32 v29, v29
	s_nop 0
	v_pk_add_f32 v[28:29], v[28:29], 1.0 op_sel_hi:[1,0]
	s_nop 0
	v_rcp_f32_e32 v28, v28
	v_rcp_f32_e32 v29, v29
	s_nop 0
	v_pk_mul_f32 v[28:29], v[30:31], v[28:29]
	s_nop 0
	v_pk_mul_f32 v[26:27], v[28:29], v[26:27]
	v_pk_mul_f32 v[28:29], v[20:21], s[30:31] op_sel_hi:[1,0]
	s_nop 0
	v_exp_f32_e32 v28, v28
	v_exp_f32_e32 v29, v29
	s_nop 0
	v_pk_add_f32 v[28:29], v[28:29], 1.0 op_sel_hi:[1,0]
	s_nop 0
	v_rcp_f32_e32 v28, v28
	v_rcp_f32_e32 v29, v29
	s_nop 0
	v_pk_mul_f32 v[20:21], v[20:21], v[28:29]
	s_nop 0
	v_pk_mul_f32 v[20:21], v[20:21], v[16:17]
	v_pk_mul_f32 v[16:17], v[22:23], s[30:31] op_sel_hi:[1,0]
	s_nop 0
	v_exp_f32_e32 v16, v16
	v_exp_f32_e32 v17, v17
	s_nop 0
	v_pk_add_f32 v[16:17], v[16:17], 1.0 op_sel_hi:[1,0]
	s_nop 0
	v_rcp_f32_e32 v16, v16
	v_rcp_f32_e32 v17, v17
	s_nop 0
	v_pk_mul_f32 v[16:17], v[22:23], v[16:17]
	s_nop 0
	v_pk_mul_f32 v[22:23], v[16:17], v[18:19]
	v_cvt_pk_bf16_f32 v16, v24, v25
	v_cvt_pk_bf16_f32 v17, v26, v27
	v_cvt_pk_bf16_f32 v18, v20, v21
	v_cvt_pk_bf16_f32 v19, v22, v23
	s_mov_b64 exec, s[40:41]
	global_store_dwordx4 v[32:33], v[16:19], off sc1
	s_mov_b64 exec, s[100:101]
	global_store_dwordx4 v[32:33], v[16:19], off
	s_mov_b64 exec, -1
	s_nop 1
	v_pk_mul_f32 v[18:19], v[12:13], s[30:31] op_sel_hi:[1,0]
	v_add_u32_e32 v16, 0xb0, v148
	v_exp_f32_e32 v18, v18
	v_exp_f32_e32 v19, v19
	v_mad_i64_i32 v[16:17], s[20:21], v16, s15, v[140:141]
	v_lshl_add_u64 v[16:17], v[16:17], 0, v[142:143]
	v_pk_add_f32 v[18:19], v[18:19], 1.0 op_sel_hi:[1,0]
	s_mov_b64 s[20:21], -1
	v_rcp_f32_e32 v18, v18
	v_rcp_f32_e32 v19, v19
	s_nop 0
	v_pk_mul_f32 v[12:13], v[12:13], v[18:19]
	s_nop 0
	v_pk_mul_f32 v[8:9], v[12:13], v[8:9]
	v_pk_mul_f32 v[12:13], v[14:15], s[30:31] op_sel_hi:[1,0]
	s_nop 0
	v_exp_f32_e32 v12, v12
	v_exp_f32_e32 v13, v13
	s_nop 0
	v_pk_add_f32 v[12:13], v[12:13], 1.0 op_sel_hi:[1,0]
	s_nop 0
	v_rcp_f32_e32 v12, v12
	v_rcp_f32_e32 v13, v13
	s_nop 0
	v_pk_mul_f32 v[12:13], v[14:15], v[12:13]
	s_nop 0
	v_pk_mul_f32 v[10:11], v[12:13], v[10:11]
	v_pk_mul_f32 v[12:13], v[4:5], s[30:31] op_sel_hi:[1,0]
	s_nop 0
	v_exp_f32_e32 v12, v12
	v_exp_f32_e32 v13, v13
	s_nop 0
	v_pk_add_f32 v[12:13], v[12:13], 1.0 op_sel_hi:[1,0]
	s_nop 0
	v_rcp_f32_e32 v12, v12
	v_rcp_f32_e32 v13, v13
	s_nop 0
	v_pk_mul_f32 v[4:5], v[4:5], v[12:13]
	s_nop 0
	v_pk_mul_f32 v[4:5], v[4:5], v[0:1]
	v_pk_mul_f32 v[0:1], v[6:7], s[30:31] op_sel_hi:[1,0]
	s_nop 0
	v_exp_f32_e32 v0, v0
	v_exp_f32_e32 v1, v1
	s_nop 0
	v_pk_add_f32 v[0:1], v[0:1], 1.0 op_sel_hi:[1,0]
	s_nop 0
	v_rcp_f32_e32 v0, v0
	v_rcp_f32_e32 v1, v1
	s_nop 0
	v_pk_mul_f32 v[0:1], v[6:7], v[0:1]
	s_nop 0
	v_pk_mul_f32 v[6:7], v[0:1], v[2:3]
	v_cvt_pk_bf16_f32 v0, v8, v9
	v_cvt_pk_bf16_f32 v1, v10, v11
	v_cvt_pk_bf16_f32 v2, v4, v5
	v_cvt_pk_bf16_f32 v3, v6, v7
	s_mov_b64 exec, s[40:41]
	global_store_dwordx4 v[16:17], v[0:3], off sc1
	s_mov_b64 exec, s[100:101]
	global_store_dwordx4 v[16:17], v[0:3], off
	s_mov_b64 exec, -1
	s_cbranch_vccnz .LBB0_236
	s_andn2_b64 vcc, exec, s[22:23]
	s_cbranch_vccnz .LBB0_235
	s_barrier
	s_branch .LBB0_235
